# scan conv: v_pk_fma_f32 on the channel pair (half the fma instructions)
# speedup vs baseline: 1.0012x; 1.0012x over previous
.Lscan1_sub:
	s_mov_b64 s[62:63], s[44:45]
	global_load_dword v82, v233, s[62:63]
	s_add_u32 s62, s62, 0x1800
	s_addc_u32 s63, s63, 0
	global_load_dword v83, v233, s[62:63]
	s_add_u32 s62, s62, 0x1800
	s_addc_u32 s63, s63, 0
	global_load_dword v84, v233, s[62:63]
	s_add_u32 s62, s62, 0x1800
	s_addc_u32 s63, s63, 0
	global_load_dword v85, v233, s[62:63]
	s_add_u32 s62, s62, 0x1800
	s_addc_u32 s63, s63, 0
	global_load_dword v86, v233, s[62:63]
	s_add_u32 s62, s62, 0x1800
	s_addc_u32 s63, s63, 0
	global_load_dword v87, v233, s[62:63]
	s_add_u32 s62, s62, 0x1800
	s_addc_u32 s63, s63, 0
	global_load_dword v88, v233, s[62:63]
	s_add_u32 s62, s62, 0x1800
	s_addc_u32 s63, s63, 0
	global_load_dword v89, v233, s[62:63]
	s_add_u32 s62, s62, 0x1800
	s_addc_u32 s63, s63, 0
	global_load_dword v90, v233, s[62:63]
	s_add_u32 s62, s62, 0x1800
	s_addc_u32 s63, s63, 0
	global_load_dword v91, v233, s[62:63]
	s_add_u32 s62, s62, 0x1800
	s_addc_u32 s63, s63, 0
	global_load_dword v92, v233, s[62:63]
	s_add_u32 s62, s62, 0x1800
	s_addc_u32 s63, s63, 0
	global_load_dword v93, v233, s[62:63]
	s_add_u32 s62, s62, 0x1800
	s_addc_u32 s63, s63, 0
	global_load_dword v94, v233, s[62:63]
	s_add_u32 s62, s62, 0x1800
	s_addc_u32 s63, s63, 0
	global_load_dword v95, v233, s[62:63]
	s_add_u32 s62, s62, 0x1800
	s_addc_u32 s63, s63, 0
	global_load_dword v96, v233, s[62:63]
	s_add_u32 s62, s62, 0x1800
	s_addc_u32 s63, s63, 0
	global_load_dword v97, v233, s[62:63]
	s_add_u32 s62, s62, 0x1800
	s_addc_u32 s63, s63, 0
	s_mov_b64 s[44:45], s[62:63]
	ds_read_b128 v[110:113], v229 offset:0
	ds_read_b128 v[122:125], v229 offset:19968
	ds_read_b128 v[114:117], v229 offset:64
	ds_read_b128 v[126:129], v229 offset:20032
	ds_read_b128 v[118:121], v229 offset:128
	ds_read_b128 v[130:133], v229 offset:20096
	ds_read_b128 v[150:153], v230
	ds_read_b128 v[154:157], v230 offset:384
	ds_read_b128 v[158:161], v230 offset:768
	s_mov_b32 s62, -1
	s_mov_b32 s63, 0xffff
	s_mov_b64 exec, s[62:63]
	v_lshlrev_b32_e32 v64, 16, v66
	v_and_b32_e32 v65, 0xffff0000, v66
	v_pk_fma_f32 v[242:243], v[58:59], v[48:49], v[56:57]
	v_lshlrev_b32_e32 v58, 16, v67
	v_and_b32_e32 v59, 0xffff0000, v67
	v_pk_fma_f32 v[244:245], v[60:61], v[48:49], v[56:57]
	v_pk_fma_f32 v[242:243], v[60:61], v[50:51], v[242:243]
	v_pk_fma_f32 v[244:245], v[62:63], v[50:51], v[244:245]
	v_pk_fma_f32 v[242:243], v[62:63], v[52:53], v[242:243]
	v_pk_fma_f32 v[244:245], v[64:65], v[52:53], v[244:245]
	v_pk_fma_f32 v[242:243], v[64:65], v[54:55], v[242:243]
	v_pk_fma_f32 v[244:245], v[58:59], v[54:55], v[244:245]
	ds_write_b64 v226, v[242:243] offset:0
	v_cvt_pk_bf16_f32 v246, v242, v243
	ds_write_b64 v226, v[244:245] offset:400
	v_cvt_pk_bf16_f32 v247, v244, v245
	ds_write_b32 v227, v246 offset:0
	ds_write_b32 v227, v247 offset:208
	v_lshlrev_b32_e32 v60, 16, v68
	v_and_b32_e32 v61, 0xffff0000, v68
	v_pk_fma_f32 v[242:243], v[62:63], v[48:49], v[56:57]
	v_lshlrev_b32_e32 v62, 16, v69
	v_and_b32_e32 v63, 0xffff0000, v69
	v_pk_fma_f32 v[244:245], v[64:65], v[48:49], v[56:57]
	v_pk_fma_f32 v[242:243], v[64:65], v[50:51], v[242:243]
	v_pk_fma_f32 v[244:245], v[58:59], v[50:51], v[244:245]
	v_pk_fma_f32 v[242:243], v[58:59], v[52:53], v[242:243]
	v_pk_fma_f32 v[244:245], v[60:61], v[52:53], v[244:245]
	v_pk_fma_f32 v[242:243], v[60:61], v[54:55], v[242:243]
	v_pk_fma_f32 v[244:245], v[62:63], v[54:55], v[244:245]
	ds_write_b64 v226, v[242:243] offset:800
	v_cvt_pk_bf16_f32 v246, v242, v243
	ds_write_b64 v226, v[244:245] offset:1200
	v_cvt_pk_bf16_f32 v247, v244, v245
	ds_write_b32 v227, v246 offset:416
	ds_write_b32 v227, v247 offset:624
	v_lshlrev_b32_e32 v64, 16, v70
	v_and_b32_e32 v65, 0xffff0000, v70
	v_pk_fma_f32 v[242:243], v[58:59], v[48:49], v[56:57]
	v_lshlrev_b32_e32 v58, 16, v71
	v_and_b32_e32 v59, 0xffff0000, v71
	v_pk_fma_f32 v[244:245], v[60:61], v[48:49], v[56:57]
	v_pk_fma_f32 v[242:243], v[60:61], v[50:51], v[242:243]
	v_pk_fma_f32 v[244:245], v[62:63], v[50:51], v[244:245]
	v_pk_fma_f32 v[242:243], v[62:63], v[52:53], v[242:243]
	v_pk_fma_f32 v[244:245], v[64:65], v[52:53], v[244:245]
	v_pk_fma_f32 v[242:243], v[64:65], v[54:55], v[242:243]
	v_pk_fma_f32 v[244:245], v[58:59], v[54:55], v[244:245]
	ds_write_b64 v226, v[242:243] offset:1600
	v_cvt_pk_bf16_f32 v246, v242, v243
	ds_write_b64 v226, v[244:245] offset:2000
	v_cvt_pk_bf16_f32 v247, v244, v245
	ds_write_b32 v227, v246 offset:832
	ds_write_b32 v227, v247 offset:1040
	v_lshlrev_b32_e32 v60, 16, v72
	v_and_b32_e32 v61, 0xffff0000, v72
	v_pk_fma_f32 v[242:243], v[62:63], v[48:49], v[56:57]
	v_lshlrev_b32_e32 v62, 16, v73
	v_and_b32_e32 v63, 0xffff0000, v73
	v_pk_fma_f32 v[244:245], v[64:65], v[48:49], v[56:57]
	v_pk_fma_f32 v[242:243], v[64:65], v[50:51], v[242:243]
	v_pk_fma_f32 v[244:245], v[58:59], v[50:51], v[244:245]
	v_pk_fma_f32 v[242:243], v[58:59], v[52:53], v[242:243]
	v_pk_fma_f32 v[244:245], v[60:61], v[52:53], v[244:245]
	v_pk_fma_f32 v[242:243], v[60:61], v[54:55], v[242:243]
	v_pk_fma_f32 v[244:245], v[62:63], v[54:55], v[244:245]
	ds_write_b64 v226, v[242:243] offset:2400
	v_cvt_pk_bf16_f32 v246, v242, v243
	ds_write_b64 v226, v[244:245] offset:2800
	v_cvt_pk_bf16_f32 v247, v244, v245
	ds_write_b32 v227, v246 offset:1248
	ds_write_b32 v227, v247 offset:1456
	v_lshlrev_b32_e32 v64, 16, v74
	v_and_b32_e32 v65, 0xffff0000, v74
	v_pk_fma_f32 v[242:243], v[58:59], v[48:49], v[56:57]
	v_lshlrev_b32_e32 v58, 16, v75
	v_and_b32_e32 v59, 0xffff0000, v75
	v_pk_fma_f32 v[244:245], v[60:61], v[48:49], v[56:57]
	v_pk_fma_f32 v[242:243], v[60:61], v[50:51], v[242:243]
	v_pk_fma_f32 v[244:245], v[62:63], v[50:51], v[244:245]
	v_pk_fma_f32 v[242:243], v[62:63], v[52:53], v[242:243]
	v_pk_fma_f32 v[244:245], v[64:65], v[52:53], v[244:245]
	v_pk_fma_f32 v[242:243], v[64:65], v[54:55], v[242:243]
	v_pk_fma_f32 v[244:245], v[58:59], v[54:55], v[244:245]
	ds_write_b64 v226, v[242:243] offset:3200
	v_cvt_pk_bf16_f32 v246, v242, v243
	ds_write_b64 v226, v[244:245] offset:3600
	v_cvt_pk_bf16_f32 v247, v244, v245
	ds_write_b32 v227, v246 offset:1664
	ds_write_b32 v227, v247 offset:1872
	v_lshlrev_b32_e32 v60, 16, v76
	v_and_b32_e32 v61, 0xffff0000, v76
	v_pk_fma_f32 v[242:243], v[62:63], v[48:49], v[56:57]
	v_lshlrev_b32_e32 v62, 16, v77
	v_and_b32_e32 v63, 0xffff0000, v77
	v_pk_fma_f32 v[244:245], v[64:65], v[48:49], v[56:57]
	v_pk_fma_f32 v[242:243], v[64:65], v[50:51], v[242:243]
	v_pk_fma_f32 v[244:245], v[58:59], v[50:51], v[244:245]
	v_pk_fma_f32 v[242:243], v[58:59], v[52:53], v[242:243]
	v_pk_fma_f32 v[244:245], v[60:61], v[52:53], v[244:245]
	v_pk_fma_f32 v[242:243], v[60:61], v[54:55], v[242:243]
	v_pk_fma_f32 v[244:245], v[62:63], v[54:55], v[244:245]
	ds_write_b64 v226, v[242:243] offset:4000
	v_cvt_pk_bf16_f32 v246, v242, v243
	ds_write_b64 v226, v[244:245] offset:4400
	v_cvt_pk_bf16_f32 v247, v244, v245
	ds_write_b32 v227, v246 offset:2080
	ds_write_b32 v227, v247 offset:2288
	v_lshlrev_b32_e32 v64, 16, v78
	v_and_b32_e32 v65, 0xffff0000, v78
	v_pk_fma_f32 v[242:243], v[58:59], v[48:49], v[56:57]
	v_lshlrev_b32_e32 v58, 16, v79
	v_and_b32_e32 v59, 0xffff0000, v79
	v_pk_fma_f32 v[244:245], v[60:61], v[48:49], v[56:57]
	v_pk_fma_f32 v[242:243], v[60:61], v[50:51], v[242:243]
	v_pk_fma_f32 v[244:245], v[62:63], v[50:51], v[244:245]
	v_pk_fma_f32 v[242:243], v[62:63], v[52:53], v[242:243]
	v_pk_fma_f32 v[244:245], v[64:65], v[52:53], v[244:245]
	v_pk_fma_f32 v[242:243], v[64:65], v[54:55], v[242:243]
	v_pk_fma_f32 v[244:245], v[58:59], v[54:55], v[244:245]
	ds_write_b64 v226, v[242:243] offset:4800
	v_cvt_pk_bf16_f32 v246, v242, v243
	ds_write_b64 v226, v[244:245] offset:5200
	v_cvt_pk_bf16_f32 v247, v244, v245
	ds_write_b32 v227, v246 offset:2496
	ds_write_b32 v227, v247 offset:2704
	v_lshlrev_b32_e32 v60, 16, v80
	v_and_b32_e32 v61, 0xffff0000, v80
	v_pk_fma_f32 v[242:243], v[62:63], v[48:49], v[56:57]
	v_lshlrev_b32_e32 v62, 16, v81
	v_and_b32_e32 v63, 0xffff0000, v81
	v_pk_fma_f32 v[244:245], v[64:65], v[48:49], v[56:57]
	v_pk_fma_f32 v[242:243], v[64:65], v[50:51], v[242:243]
	v_pk_fma_f32 v[244:245], v[58:59], v[50:51], v[244:245]
	v_pk_fma_f32 v[242:243], v[58:59], v[52:53], v[242:243]
	v_pk_fma_f32 v[244:245], v[60:61], v[52:53], v[244:245]
	v_pk_fma_f32 v[242:243], v[60:61], v[54:55], v[242:243]
	v_pk_fma_f32 v[244:245], v[62:63], v[54:55], v[244:245]
	ds_write_b64 v226, v[242:243] offset:5600
	v_cvt_pk_bf16_f32 v246, v242, v243
	ds_write_b64 v226, v[244:245] offset:6000
	v_cvt_pk_bf16_f32 v247, v244, v245
	ds_write_b32 v227, v246 offset:2912
	ds_write_b32 v227, v247 offset:3120
	s_mov_b64 exec, -1
	s_waitcnt lgkmcnt(0)
	ds_read_b128 v[98:101], v228 offset:0
	ds_read_b128 v[102:105], v228 offset:64
	ds_read_b128 v[106:109], v228 offset:128
	ds_read_b128 v[162:165], v231
	s_waitcnt lgkmcnt(0)
	v_mfma_f32_16x16x32_bf16 v[134:137], v[110:113], v[98:101], 0
	v_mfma_f32_16x16x32_bf16 v[138:141], v[122:125], v[98:101], 0
	v_mfma_f32_16x16x32_bf16 v[134:137], v[114:117], v[102:105], v[134:137]
	v_mfma_f32_16x16x32_bf16 v[138:141], v[126:129], v[102:105], v[138:141]
	v_mfma_f32_16x16x32_bf16 v[134:137], v[118:121], v[106:109], v[134:137]
	v_mfma_f32_16x16x32_bf16 v[138:141], v[130:133], v[106:109], v[138:141]
	ds_read_b128 v[110:113], v229 offset:3328
	ds_read_b128 v[122:125], v229 offset:23296
	ds_read_b128 v[114:117], v229 offset:3392
	ds_read_b128 v[126:129], v229 offset:23360
	ds_read_b128 v[118:121], v229 offset:3456
	ds_read_b128 v[130:133], v229 offset:23424
	s_nop 7
	s_nop 7
	v_fmamk_f32 v166, v134, 0xbfb8aa3b, v150
	v_fmamk_f32 v204, v135, 0xbfb8aa3b, v151
	v_fmamk_f32 v210, v136, 0xbfb8aa3b, v152
	v_fmamk_f32 v216, v137, 0xbfb8aa3b, v153
	v_fmamk_f32 v167, v138, 0xbfb8aa3b, v154
	v_fmamk_f32 v205, v139, 0xbfb8aa3b, v155
	v_fmamk_f32 v211, v140, 0xbfb8aa3b, v156
	v_fmamk_f32 v217, v141, 0xbfb8aa3b, v157
	v_exp_f32_e32 v166, v166
	v_exp_f32_e32 v204, v204
	v_exp_f32_e32 v210, v210
	v_exp_f32_e32 v216, v216
	v_exp_f32_e32 v167, v167
	v_exp_f32_e32 v205, v205
	v_exp_f32_e32 v211, v211
	v_exp_f32_e32 v217, v217
	v_add_f32_e32 v166, 1.0, v166
	v_add_f32_e32 v204, 1.0, v204
	v_add_f32_e32 v210, 1.0, v210
	v_add_f32_e32 v216, 1.0, v216
	v_add_f32_e32 v167, 1.0, v167
	v_add_f32_e32 v205, 1.0, v205
	v_add_f32_e32 v211, 1.0, v211
	v_add_f32_e32 v217, 1.0, v217
	v_rcp_f32_e32 v166, v166
	v_rcp_f32_e32 v204, v204
	v_rcp_f32_e32 v210, v210
	v_rcp_f32_e32 v216, v216
	v_rcp_f32_e32 v167, v167
	v_rcp_f32_e32 v205, v205
	v_rcp_f32_e32 v211, v211
	v_rcp_f32_e32 v217, v217
	v_mul_f32_e32 v168, v158, v166
	v_mul_f32_e32 v206, v159, v204
	v_mul_f32_e32 v212, v160, v210
	v_mul_f32_e32 v218, v161, v216
	v_mul_f32_e32 v167, v162, v167
	v_mul_f32_e32 v205, v163, v205
	v_mul_f32_e32 v211, v164, v211
	v_mul_f32_e32 v217, v165, v217
	ds_read_b128 v[150:153], v230 offset:64
	ds_read_b128 v[154:157], v230 offset:448
	ds_read_b128 v[158:161], v230 offset:832
	ds_read_b128 v[162:165], v231 offset:64
	v_exp_f32_e32 v166, v168
	v_exp_f32_e32 v204, v206
	v_exp_f32_e32 v210, v212
	v_exp_f32_e32 v216, v218
	v_fmaak_f32 v170, v168, v248, 0xbe1d955b
	v_fmaak_f32 v208, v206, v248, 0xbe1d955b
	v_fmaak_f32 v214, v212, v248, 0xbe1d955b
	v_fmaak_f32 v220, v218, v248, 0xbe1d955b
	v_fmaak_f32 v170, v168, v170, 0xbee35847
	v_fmaak_f32 v208, v206, v208, 0xbee35847
	v_fmaak_f32 v214, v212, v214, 0xbee35847
	v_fmaak_f32 v220, v218, v220, 0xbee35847
	v_min3_f32 v169, v168, v206, v212
	v_fmaak_f32 v170, v168, v170, 0xbf75fdf0
	v_fmaak_f32 v208, v206, v208, 0xbf75fdf0
	v_fmaak_f32 v214, v212, v214, 0xbf75fdf0
	v_fmaak_f32 v220, v218, v220, 0xbf75fdf0
	v_min_f32_e32 v169, v169, v218
	v_fmaak_f32 v170, v168, v170, 0xbfb17218
	v_fmaak_f32 v208, v206, v208, 0xbfb17218
	v_fmaak_f32 v214, v212, v214, 0xbfb17218
	v_fmaak_f32 v220, v218, v220, 0xbfb17218
	v_cmp_nlt_f32_e32 vcc, 0xbe38aa3b, v169
	v_mul_f32_e32 v170, v170, v168
	v_mul_f32_e32 v208, v208, v206
	v_mul_f32_e32 v214, v214, v212
	v_mul_f32_e32 v220, v220, v218
	s_cbranch_vccnz .Lscan1_far0

.Lscan2_sub:
	global_load_dwordx2 v[24:25], v235, s[6:7] offset:0
	global_load_dwordx2 v[26:27], v235, s[6:7] offset:32
	global_load_dwordx2 v[28:29], v235, s[6:7] offset:64
	global_load_dwordx2 v[30:31], v235, s[6:7] offset:96
	global_load_dwordx2 v[32:33], v235, s[6:7] offset:128
	global_load_dwordx2 v[34:35], v235, s[6:7] offset:160
	s_mov_b64 s[62:63], s[44:45]
	global_load_dword v82, v233, s[62:63]
	s_add_u32 s62, s62, 0x1800
	s_addc_u32 s63, s63, 0
	global_load_dword v83, v233, s[62:63]
	s_add_u32 s62, s62, 0x1800
	s_addc_u32 s63, s63, 0
	global_load_dword v84, v233, s[62:63]
	s_add_u32 s62, s62, 0x1800
	s_addc_u32 s63, s63, 0
	global_load_dword v85, v233, s[62:63]
	s_add_u32 s62, s62, 0x1800
	s_addc_u32 s63, s63, 0
	global_load_dword v86, v233, s[62:63]
	s_add_u32 s62, s62, 0x1800
	s_addc_u32 s63, s63, 0
	global_load_dword v87, v233, s[62:63]
	s_add_u32 s62, s62, 0x1800
	s_addc_u32 s63, s63, 0
	global_load_dword v88, v233, s[62:63]
	s_add_u32 s62, s62, 0x1800
	s_addc_u32 s63, s63, 0
	global_load_dword v89, v233, s[62:63]
	s_add_u32 s62, s62, 0x1800
	s_addc_u32 s63, s63, 0
	global_load_dword v90, v233, s[62:63]
	s_add_u32 s62, s62, 0x1800
	s_addc_u32 s63, s63, 0
	global_load_dword v91, v233, s[62:63]
	s_add_u32 s62, s62, 0x1800
	s_addc_u32 s63, s63, 0
	global_load_dword v92, v233, s[62:63]
	s_add_u32 s62, s62, 0x1800
	s_addc_u32 s63, s63, 0
	global_load_dword v93, v233, s[62:63]
	s_add_u32 s62, s62, 0x1800
	s_addc_u32 s63, s63, 0
	global_load_dword v94, v233, s[62:63]
	s_add_u32 s62, s62, 0x1800
	s_addc_u32 s63, s63, 0
	global_load_dword v95, v233, s[62:63]
	s_add_u32 s62, s62, 0x1800
	s_addc_u32 s63, s63, 0
	global_load_dword v96, v233, s[62:63]
	s_add_u32 s62, s62, 0x1800
	s_addc_u32 s63, s63, 0
	global_load_dword v97, v233, s[62:63]
	s_add_u32 s62, s62, 0x1800
	s_addc_u32 s63, s63, 0
	s_mov_b64 s[44:45], s[62:63]
	ds_read_b128 v[110:113], v229 offset:0
	ds_read_b128 v[122:125], v229 offset:19968
	ds_read_b128 v[114:117], v229 offset:64
	ds_read_b128 v[126:129], v229 offset:20032
	ds_read_b128 v[118:121], v229 offset:128
	ds_read_b128 v[130:133], v229 offset:20096
	ds_read_b128 v[150:153], v230
	ds_read_b128 v[154:157], v230 offset:384
	ds_read_b128 v[158:161], v230 offset:768
	s_mov_b32 s62, -1
	s_mov_b32 s63, 0xffff
	s_mov_b64 exec, s[62:63]
	v_lshlrev_b32_e32 v64, 16, v66
	v_and_b32_e32 v65, 0xffff0000, v66
	v_pk_fma_f32 v[242:243], v[58:59], v[48:49], v[56:57]
	v_lshlrev_b32_e32 v58, 16, v67
	v_and_b32_e32 v59, 0xffff0000, v67
	v_pk_fma_f32 v[244:245], v[60:61], v[48:49], v[56:57]
	v_pk_fma_f32 v[242:243], v[60:61], v[50:51], v[242:243]
	v_pk_fma_f32 v[244:245], v[62:63], v[50:51], v[244:245]
	v_pk_fma_f32 v[242:243], v[62:63], v[52:53], v[242:243]
	v_pk_fma_f32 v[244:245], v[64:65], v[52:53], v[244:245]
	v_pk_fma_f32 v[242:243], v[64:65], v[54:55], v[242:243]
	v_pk_fma_f32 v[244:245], v[58:59], v[54:55], v[244:245]
	ds_write_b64 v226, v[242:243] offset:0
	v_cvt_pk_bf16_f32 v246, v242, v243
	ds_write_b64 v226, v[244:245] offset:400
	v_cvt_pk_bf16_f32 v247, v244, v245
	ds_write_b32 v227, v246 offset:0
	ds_write_b32 v227, v247 offset:208
	v_lshlrev_b32_e32 v60, 16, v68
	v_and_b32_e32 v61, 0xffff0000, v68
	v_pk_fma_f32 v[242:243], v[62:63], v[48:49], v[56:57]
	v_lshlrev_b32_e32 v62, 16, v69
	v_and_b32_e32 v63, 0xffff0000, v69
	v_pk_fma_f32 v[244:245], v[64:65], v[48:49], v[56:57]
	v_pk_fma_f32 v[242:243], v[64:65], v[50:51], v[242:243]
	v_pk_fma_f32 v[244:245], v[58:59], v[50:51], v[244:245]
	v_pk_fma_f32 v[242:243], v[58:59], v[52:53], v[242:243]
	v_pk_fma_f32 v[244:245], v[60:61], v[52:53], v[244:245]
	v_pk_fma_f32 v[242:243], v[60:61], v[54:55], v[242:243]
	v_pk_fma_f32 v[244:245], v[62:63], v[54:55], v[244:245]
	ds_write_b64 v226, v[242:243] offset:800
	v_cvt_pk_bf16_f32 v246, v242, v243
	ds_write_b64 v226, v[244:245] offset:1200
	v_cvt_pk_bf16_f32 v247, v244, v245
	ds_write_b32 v227, v246 offset:416
	ds_write_b32 v227, v247 offset:624
	v_lshlrev_b32_e32 v64, 16, v70
	v_and_b32_e32 v65, 0xffff0000, v70
	v_pk_fma_f32 v[242:243], v[58:59], v[48:49], v[56:57]
	v_lshlrev_b32_e32 v58, 16, v71
	v_and_b32_e32 v59, 0xffff0000, v71
	v_pk_fma_f32 v[244:245], v[60:61], v[48:49], v[56:57]
	v_pk_fma_f32 v[242:243], v[60:61], v[50:51], v[242:243]
	v_pk_fma_f32 v[244:245], v[62:63], v[50:51], v[244:245]
	v_pk_fma_f32 v[242:243], v[62:63], v[52:53], v[242:243]
	v_pk_fma_f32 v[244:245], v[64:65], v[52:53], v[244:245]
	v_pk_fma_f32 v[242:243], v[64:65], v[54:55], v[242:243]
	v_pk_fma_f32 v[244:245], v[58:59], v[54:55], v[244:245]
	ds_write_b64 v226, v[242:243] offset:1600
	v_cvt_pk_bf16_f32 v246, v242, v243
	ds_write_b64 v226, v[244:245] offset:2000
	v_cvt_pk_bf16_f32 v247, v244, v245
	ds_write_b32 v227, v246 offset:832
	ds_write_b32 v227, v247 offset:1040
	v_lshlrev_b32_e32 v60, 16, v72
	v_and_b32_e32 v61, 0xffff0000, v72
	v_pk_fma_f32 v[242:243], v[62:63], v[48:49], v[56:57]
	v_lshlrev_b32_e32 v62, 16, v73
	v_and_b32_e32 v63, 0xffff0000, v73
	v_pk_fma_f32 v[244:245], v[64:65], v[48:49], v[56:57]
	v_pk_fma_f32 v[242:243], v[64:65], v[50:51], v[242:243]
	v_pk_fma_f32 v[244:245], v[58:59], v[50:51], v[244:245]
	v_pk_fma_f32 v[242:243], v[58:59], v[52:53], v[242:243]
	v_pk_fma_f32 v[244:245], v[60:61], v[52:53], v[244:245]
	v_pk_fma_f32 v[242:243], v[60:61], v[54:55], v[242:243]
	v_pk_fma_f32 v[244:245], v[62:63], v[54:55], v[244:245]
	ds_write_b64 v226, v[242:243] offset:2400
	v_cvt_pk_bf16_f32 v246, v242, v243
	ds_write_b64 v226, v[244:245] offset:2800
	v_cvt_pk_bf16_f32 v247, v244, v245
	ds_write_b32 v227, v246 offset:1248
	ds_write_b32 v227, v247 offset:1456
	v_lshlrev_b32_e32 v64, 16, v74
	v_and_b32_e32 v65, 0xffff0000, v74
	v_pk_fma_f32 v[242:243], v[58:59], v[48:49], v[56:57]
	v_lshlrev_b32_e32 v58, 16, v75
	v_and_b32_e32 v59, 0xffff0000, v75
	v_pk_fma_f32 v[244:245], v[60:61], v[48:49], v[56:57]
	v_pk_fma_f32 v[242:243], v[60:61], v[50:51], v[242:243]
	v_pk_fma_f32 v[244:245], v[62:63], v[50:51], v[244:245]
	v_pk_fma_f32 v[242:243], v[62:63], v[52:53], v[242:243]
	v_pk_fma_f32 v[244:245], v[64:65], v[52:53], v[244:245]
	v_pk_fma_f32 v[242:243], v[64:65], v[54:55], v[242:243]
	v_pk_fma_f32 v[244:245], v[58:59], v[54:55], v[244:245]
	ds_write_b64 v226, v[242:243] offset:3200
	v_cvt_pk_bf16_f32 v246, v242, v243
	ds_write_b64 v226, v[244:245] offset:3600
	v_cvt_pk_bf16_f32 v247, v244, v245
	ds_write_b32 v227, v246 offset:1664
	ds_write_b32 v227, v247 offset:1872
	v_lshlrev_b32_e32 v60, 16, v76
	v_and_b32_e32 v61, 0xffff0000, v76
	v_pk_fma_f32 v[242:243], v[62:63], v[48:49], v[56:57]
	v_lshlrev_b32_e32 v62, 16, v77
	v_and_b32_e32 v63, 0xffff0000, v77
	v_pk_fma_f32 v[244:245], v[64:65], v[48:49], v[56:57]
	v_pk_fma_f32 v[242:243], v[64:65], v[50:51], v[242:243]
	v_pk_fma_f32 v[244:245], v[58:59], v[50:51], v[244:245]
	v_pk_fma_f32 v[242:243], v[58:59], v[52:53], v[242:243]
	v_pk_fma_f32 v[244:245], v[60:61], v[52:53], v[244:245]
	v_pk_fma_f32 v[242:243], v[60:61], v[54:55], v[242:243]
	v_pk_fma_f32 v[244:245], v[62:63], v[54:55], v[244:245]
	ds_write_b64 v226, v[242:243] offset:4000
	v_cvt_pk_bf16_f32 v246, v242, v243
	ds_write_b64 v226, v[244:245] offset:4400
	v_cvt_pk_bf16_f32 v247, v244, v245
	ds_write_b32 v227, v246 offset:2080
	ds_write_b32 v227, v247 offset:2288
	v_lshlrev_b32_e32 v64, 16, v78
	v_and_b32_e32 v65, 0xffff0000, v78
	v_pk_fma_f32 v[242:243], v[58:59], v[48:49], v[56:57]
	v_lshlrev_b32_e32 v58, 16, v79
	v_and_b32_e32 v59, 0xffff0000, v79
	v_pk_fma_f32 v[244:245], v[60:61], v[48:49], v[56:57]
	v_pk_fma_f32 v[242:243], v[60:61], v[50:51], v[242:243]
	v_pk_fma_f32 v[244:245], v[62:63], v[50:51], v[244:245]
	v_pk_fma_f32 v[242:243], v[62:63], v[52:53], v[242:243]
	v_pk_fma_f32 v[244:245], v[64:65], v[52:53], v[244:245]
	v_pk_fma_f32 v[242:243], v[64:65], v[54:55], v[242:243]
	v_pk_fma_f32 v[244:245], v[58:59], v[54:55], v[244:245]
	ds_write_b64 v226, v[242:243] offset:4800
	v_cvt_pk_bf16_f32 v246, v242, v243
	ds_write_b64 v226, v[244:245] offset:5200
	v_cvt_pk_bf16_f32 v247, v244, v245
	ds_write_b32 v227, v246 offset:2496
	ds_write_b32 v227, v247 offset:2704
	v_lshlrev_b32_e32 v60, 16, v80
	v_and_b32_e32 v61, 0xffff0000, v80
	v_pk_fma_f32 v[242:243], v[62:63], v[48:49], v[56:57]
	v_lshlrev_b32_e32 v62, 16, v81
	v_and_b32_e32 v63, 0xffff0000, v81
	v_pk_fma_f32 v[244:245], v[64:65], v[48:49], v[56:57]
	v_pk_fma_f32 v[242:243], v[64:65], v[50:51], v[242:243]
	v_pk_fma_f32 v[244:245], v[58:59], v[50:51], v[244:245]
	v_pk_fma_f32 v[242:243], v[58:59], v[52:53], v[242:243]
	v_pk_fma_f32 v[244:245], v[60:61], v[52:53], v[244:245]
	v_pk_fma_f32 v[242:243], v[60:61], v[54:55], v[242:243]
	v_pk_fma_f32 v[244:245], v[62:63], v[54:55], v[244:245]
	ds_write_b64 v226, v[242:243] offset:5600
	v_cvt_pk_bf16_f32 v246, v242, v243
	ds_write_b64 v226, v[244:245] offset:6000
	v_cvt_pk_bf16_f32 v247, v244, v245
	ds_write_b32 v227, v246 offset:2912
	ds_write_b32 v227, v247 offset:3120
	s_mov_b64 exec, -1
	s_waitcnt lgkmcnt(0)
	ds_read_b128 v[98:101], v228 offset:0
	ds_read_b128 v[102:105], v228 offset:64
	ds_read_b128 v[106:109], v228 offset:128
	ds_read_b128 v[162:165], v231
	s_waitcnt lgkmcnt(0)
	v_mfma_f32_16x16x32_bf16 v[134:137], v[110:113], v[98:101], 0
	v_mfma_f32_16x16x32_bf16 v[138:141], v[122:125], v[98:101], 0
	v_mfma_f32_16x16x32_bf16 v[134:137], v[114:117], v[102:105], v[134:137]
	v_mfma_f32_16x16x32_bf16 v[138:141], v[126:129], v[102:105], v[138:141]
	v_mfma_f32_16x16x32_bf16 v[134:137], v[118:121], v[106:109], v[134:137]
	v_mfma_f32_16x16x32_bf16 v[138:141], v[130:133], v[106:109], v[138:141]
	ds_read_b128 v[110:113], v229 offset:3328
	ds_read_b128 v[122:125], v229 offset:23296
	ds_read_b128 v[114:117], v229 offset:3392
	ds_read_b128 v[126:129], v229 offset:23360
	ds_read_b128 v[118:121], v229 offset:3456
	ds_read_b128 v[130:133], v229 offset:23424
	s_nop 7
	s_nop 7
	v_fmamk_f32 v166, v134, 0xbfb8aa3b, v150
	v_fmamk_f32 v204, v135, 0xbfb8aa3b, v151
	v_fmamk_f32 v210, v136, 0xbfb8aa3b, v152
	v_fmamk_f32 v216, v137, 0xbfb8aa3b, v153
	v_fmamk_f32 v167, v138, 0xbfb8aa3b, v154
	v_fmamk_f32 v205, v139, 0xbfb8aa3b, v155
	v_fmamk_f32 v211, v140, 0xbfb8aa3b, v156
	v_fmamk_f32 v217, v141, 0xbfb8aa3b, v157
	v_exp_f32_e32 v166, v166
	v_exp_f32_e32 v204, v204
	v_exp_f32_e32 v210, v210
	v_exp_f32_e32 v216, v216
	v_exp_f32_e32 v167, v167
	v_exp_f32_e32 v205, v205
	v_exp_f32_e32 v211, v211
	v_exp_f32_e32 v217, v217
	v_add_f32_e32 v166, 1.0, v166
	v_add_f32_e32 v204, 1.0, v204
	v_add_f32_e32 v210, 1.0, v210
	v_add_f32_e32 v216, 1.0, v216
	v_add_f32_e32 v167, 1.0, v167
	v_add_f32_e32 v205, 1.0, v205
	v_add_f32_e32 v211, 1.0, v211
	v_add_f32_e32 v217, 1.0, v217
	v_rcp_f32_e32 v166, v166
	v_rcp_f32_e32 v204, v204
	v_rcp_f32_e32 v210, v210
	v_rcp_f32_e32 v216, v216
	v_rcp_f32_e32 v167, v167
	v_rcp_f32_e32 v205, v205
	v_rcp_f32_e32 v211, v211
	v_rcp_f32_e32 v217, v217
	v_mul_f32_e32 v168, v158, v166
	v_mul_f32_e32 v206, v159, v204
	v_mul_f32_e32 v212, v160, v210
	v_mul_f32_e32 v218, v161, v216
	v_mul_f32_e32 v167, v162, v167
	v_mul_f32_e32 v205, v163, v205
	v_mul_f32_e32 v211, v164, v211
	v_mul_f32_e32 v217, v165, v217
	ds_read_b128 v[150:153], v230 offset:64
	ds_read_b128 v[154:157], v230 offset:448
	ds_read_b128 v[158:161], v230 offset:832
	ds_read_b128 v[162:165], v231 offset:64
	v_exp_f32_e32 v166, v168
	v_exp_f32_e32 v204, v206
	v_exp_f32_e32 v210, v212
	v_exp_f32_e32 v216, v218
	v_fmaak_f32 v170, v168, v248, 0xbe1d955b
	v_fmaak_f32 v208, v206, v248, 0xbe1d955b
	v_fmaak_f32 v214, v212, v248, 0xbe1d955b
	v_fmaak_f32 v220, v218, v248, 0xbe1d955b
	v_fmaak_f32 v170, v168, v170, 0xbee35847
	v_fmaak_f32 v208, v206, v208, 0xbee35847
	v_fmaak_f32 v214, v212, v214, 0xbee35847
	v_fmaak_f32 v220, v218, v220, 0xbee35847
	v_min3_f32 v169, v168, v206, v212
	v_fmaak_f32 v170, v168, v170, 0xbf75fdf0
	v_fmaak_f32 v208, v206, v208, 0xbf75fdf0
	v_fmaak_f32 v214, v212, v214, 0xbf75fdf0
	v_fmaak_f32 v220, v218, v220, 0xbf75fdf0
	v_min_f32_e32 v169, v169, v218
	v_fmaak_f32 v170, v168, v170, 0xbfb17218
	v_fmaak_f32 v208, v206, v208, 0xbfb17218
	v_fmaak_f32 v214, v212, v214, 0xbfb17218
	v_fmaak_f32 v220, v218, v220, 0xbfb17218
	v_cmp_nlt_f32_e32 vcc, 0xbe38aa3b, v169
	v_mul_f32_e32 v170, v170, v168
	v_mul_f32_e32 v208, v208, v206
	v_mul_f32_e32 v214, v214, v212
	v_mul_f32_e32 v220, v220, v218
	s_cbranch_vccnz .Lscan2_far0
